# sliding-window interior tile software-pipelined inside the wave like the selected-branch tile
# baseline (speedup 1.0000x reference)
; #define LAS __attribute__((address_space(3)))
; template <int BR>
; DI void attn_branch(const AttnCtx& c, unsigned long long tmask, const bf16_t* kbase, size_t kpitch, const bf16_t* vbase, size_t vpitch, f32x16 (&o)[2], float& lsum) {
;     ...
;             else interior = (jc * 64 + 63 <= c.tw) && (jc * 64 > c.tw + 31 - 512);
;             if (interior) {
;                 f32x16 s0, s1;
; #pragma unroll
;                 for (int i = 0; i < 16; ++i) { s0[i] = sbias; s1[i] = sbias; }
; #pragma unroll
;                 for (int st = 0; st < 4; ++st) {
;                     const bf16x8 kf0 = *(const LAS bf16x8*)(Ks + c.qi * 72 + 16 * st + 8 * c.hi), kf1 = *(const LAS bf16x8*)(Ks + (32 + c.qi) * 72 + 16 * st + 8 * c.hi);
;                     s0 = MFMA32(kf0, c.q[st], s0); s1 = MFMA32(kf1, c.q[st], s1);
;                 }
;                 float p0[16], p1[16];
; #pragma unroll
;                 for (int i = 0; i < 16; ++i) { p0[i] = __builtin_amdgcn_exp2f(s0[i]); p1[i] = __builtin_amdgcn_exp2f(s1[i]); }
;                 {
;                     float l0 = 0.f, l1 = 0.f;
; #pragma unroll
;                     for (int i = 0; i < 16; ++i) { l0 += p0[i]; l1 += p1[i]; }
;                     lsum += l0 + l1;
;                 }
;                 if (BR == 1) {
; #pragma unroll
;                     for (int gq = 0; gq < 4; ++gq) {
;                         const int jj = jc * 16 + gq * 2 + c.hi;
;                         __hip_atomic_fetch_add(c.impw + jj, (p0[4 * gq] + p0[4 * gq + 1]) + (p0[4 * gq + 2] + p0[4 * gq + 3]), __ATOMIC_RELAXED, __HIP_MEMORY_SCOPE_WORKGROUP);
;                         __hip_atomic_fetch_add(c.impw + jj + 1, p0[4 * gq + 3], __ATOMIC_RELAXED, __HIP_MEMORY_SCOPE_WORKGROUP);
;                     }
; #pragma unroll
;                     for (int gq = 0; gq < 4; ++gq) {
;                         const int jj = jc * 16 + 8 + gq * 2 + c.hi;
;                         __hip_atomic_fetch_add(c.impw + jj, (p1[4 * gq] + p1[4 * gq + 1]) + (p1[4 * gq + 2] + p1[4 * gq + 3]), __ATOMIC_RELAXED, __HIP_MEMORY_SCOPE_WORKGROUP);
;                         if (jj + 1 < 64) __hip_atomic_fetch_add(c.impw + jj + 1, p1[4 * gq + 3], __ATOMIC_RELAXED, __HIP_MEMORY_SCOPE_WORKGROUP);
;                     }
;                 }
;                 if (BR != 0) {
;                     unsigned pa[8], pb[8];
; #pragma unroll
.LBB0_403:
	v_lshlrev_b32_e32 v96, 1, v170
	v_add3_u32 v201, s11, v185, v96
	ds_read_b128 v[212:215], v201
	ds_read_b128 v[216:219], v201 offset:4608
	ds_read_b128 v[220:223], v201 offset:32
	ds_read_b128 v[224:227], v201 offset:4640
	ds_read_b128 v[228:231], v201 offset:64
	ds_read_b128 v[232:235], v201 offset:4672
	ds_read_b128 v[236:239], v201 offset:96
	ds_read_b128 v[240:243], v201 offset:4704
	s_waitcnt lgkmcnt(7)
	v_mfma_f32_32x32x16_bf16 v[96:111], v[212:215], v[130:133], 0
	s_waitcnt lgkmcnt(5)
	v_mfma_f32_32x32x16_bf16 v[96:111], v[220:223], v[134:137], v[96:111]
	s_waitcnt lgkmcnt(3)
	v_mfma_f32_32x32x16_bf16 v[96:111], v[228:231], v[138:141], v[96:111]
	s_waitcnt lgkmcnt(1)
	v_mfma_f32_32x32x16_bf16 v[96:111], v[236:239], v[142:145], v[96:111]
	s_waitcnt lgkmcnt(0)
	v_mfma_f32_32x32x16_bf16 v[112:127], v[216:219], v[130:133], 0
	v_mfma_f32_32x32x16_bf16 v[112:127], v[224:227], v[134:137], v[112:127]
	s_nop 9
	v_exp_f32_e32 v96, v96
	v_exp_f32_e32 v97, v97
	v_exp_f32_e32 v98, v98
	v_mfma_f32_32x32x16_bf16 v[112:127], v[232:235], v[138:141], v[112:127]
	v_exp_f32_e32 v99, v99
	v_exp_f32_e32 v100, v100
	v_exp_f32_e32 v101, v101
	v_mfma_f32_32x32x16_bf16 v[112:127], v[240:243], v[142:145], v[112:127]
	v_add3_u32 v251, s11, v186, v170
	v_add_u32_e32 v255, 0x2000, v251
	v_add_u32_e32 v251, 0x3000, v251
	ds_read2_b64 v[212:215], v255 offset0:128 offset1:130
	ds_read2_b64 v[216:219], v251 offset0:160 offset1:162
	ds_read2_b64 v[220:223], v255 offset0:132 offset1:134
	ds_read2_b64 v[224:227], v251 offset0:164 offset1:166
	ds_read2_b64 v[228:231], v255 offset0:136 offset1:138
	ds_read2_b64 v[232:235], v251 offset0:168 offset1:170
	ds_read2_b64 v[236:239], v255 offset0:140 offset1:142
	ds_read2_b64 v[240:243], v251 offset0:172 offset1:174
	v_exp_f32_e32 v102, v102
	v_exp_f32_e32 v103, v103
	v_exp_f32_e32 v104, v104
	v_exp_f32_e32 v105, v105
	v_exp_f32_e32 v106, v106
	v_exp_f32_e32 v107, v107
	v_exp_f32_e32 v108, v108
	v_exp_f32_e32 v109, v109
	v_exp_f32_e32 v110, v110
	v_exp_f32_e32 v111, v111
	v_pk_add_f32 v[252:253], v[96:97], v[98:99]
	v_pk_add_f32 v[252:253], v[100:101], v[252:253]
	v_pk_add_f32 v[252:253], v[102:103], v[252:253]
	v_pk_add_f32 v[252:253], v[104:105], v[252:253]
	v_pk_add_f32 v[252:253], v[106:107], v[252:253]
	v_pk_add_f32 v[252:253], v[108:109], v[252:253]
	v_pk_add_f32 v[252:253], v[110:111], v[252:253]
	v_cvt_pk_bf16_f32 v202, v96, v97
	v_cvt_pk_bf16_f32 v203, v98, v99
	v_cvt_pk_bf16_f32 v204, v100, v101
	v_cvt_pk_bf16_f32 v205, v102, v103
	v_cvt_pk_bf16_f32 v206, v104, v105
	v_cvt_pk_bf16_f32 v207, v106, v107
	v_cvt_pk_bf16_f32 v208, v108, v109
	v_cvt_pk_bf16_f32 v209, v110, v111
	s_waitcnt lgkmcnt(0)
	v_mfma_f32_32x32x16_bf16 v[80:95], v[212:215], v[202:205], v[80:95]
	v_exp_f32_e32 v112, v112
	v_exp_f32_e32 v113, v113
	v_exp_f32_e32 v114, v114
	v_exp_f32_e32 v115, v115
	v_mfma_f32_32x32x16_bf16 v[64:79], v[216:219], v[202:205], v[64:79]
	v_exp_f32_e32 v116, v116
	v_exp_f32_e32 v117, v117
	v_exp_f32_e32 v118, v118
	v_exp_f32_e32 v119, v119
	v_mfma_f32_32x32x16_bf16 v[80:95], v[220:223], v[206:209], v[80:95]
	v_exp_f32_e32 v120, v120
	v_exp_f32_e32 v121, v121
	v_exp_f32_e32 v122, v122
	v_exp_f32_e32 v123, v123
	v_mfma_f32_32x32x16_bf16 v[64:79], v[224:227], v[206:209], v[64:79]
	v_exp_f32_e32 v124, v124
	v_exp_f32_e32 v125, v125
	v_exp_f32_e32 v126, v126
	v_exp_f32_e32 v127, v127
	v_pk_add_f32 v[252:253], v[112:113], v[252:253]
	v_pk_add_f32 v[252:253], v[114:115], v[252:253]
	v_pk_add_f32 v[252:253], v[116:117], v[252:253]
	v_pk_add_f32 v[252:253], v[118:119], v[252:253]
	v_pk_add_f32 v[252:253], v[120:121], v[252:253]
	v_pk_add_f32 v[252:253], v[122:123], v[252:253]
	v_pk_add_f32 v[252:253], v[124:125], v[252:253]
	v_pk_add_f32 v[252:253], v[126:127], v[252:253]
	v_cvt_pk_bf16_f32 v96, v112, v113
	v_cvt_pk_bf16_f32 v97, v114, v115
	v_cvt_pk_bf16_f32 v98, v116, v117
	v_cvt_pk_bf16_f32 v99, v118, v119
	v_cvt_pk_bf16_f32 v100, v120, v121
	v_cvt_pk_bf16_f32 v101, v122, v123
	v_cvt_pk_bf16_f32 v102, v124, v125
	v_cvt_pk_bf16_f32 v103, v126, v127
	v_add_f32_e32 v252, v252, v253
	v_add_f32_e32 v174, v174, v252
	v_mfma_f32_32x32x16_bf16 v[80:95], v[228:231], v[96:99], v[80:95]
	v_mfma_f32_32x32x16_bf16 v[64:79], v[232:235], v[96:99], v[64:79]
	v_mfma_f32_32x32x16_bf16 v[80:95], v[236:239], v[100:103], v[80:95]
	v_mfma_f32_32x32x16_bf16 v[64:79], v[240:243], v[100:103], v[64:79]
	s_or_b64 exec, exec, s[0:1]
	s_andn2_b64 vcc, exec, s[4:5]
	s_xor_b64 s[2:3], s[2:3], -1
	s_cbranch_vccz .LBB0_306
